# stack of individually validated micro-edits on top: hyena step-1 load overlap, G1 accumulator-init elision, FFT-code v_pk_mov_b32 pair moves
# speedup vs baseline: 1.0011x; 1.0011x over previous
.Lmy_hy1_p2:
	v_pk_mov_b32 v[2:3], v[40:41], v[40:41] op_sel:[0,1]
	s_nop 0
	v_pk_mov_b32 v[4:5], v[42:43], v[42:43] op_sel:[0,1]
	s_nop 0
	v_pk_mov_b32 v[6:7], v[44:45], v[44:45] op_sel:[0,1]
	v_pk_mov_b32 v[8:9], v[46:47], v[46:47] op_sel:[0,1]
	v_mov_b32_e32 v27, v48
	v_mov_b32_e32 v25, v49
	s_mov_b64 s[72:73], exec

.LBB0_528:
	v_pk_mov_b32 v[2:3], v[40:41], v[40:41] op_sel:[0,1]
	s_nop 0
	v_pk_mov_b32 v[4:5], v[42:43], v[42:43] op_sel:[0,1]
	v_pk_mov_b32 v[6:7], v[44:45], v[44:45] op_sel:[0,1]
	v_pk_mov_b32 v[8:9], v[46:47], v[46:47] op_sel:[0,1]
	v_mov_b32_e32 v27, v48
	v_mov_b32_e32 v25, v49
	v_add_u32_e32 v32, 0x200, v18
	s_mov_b64 s[64:65], exec
	s_branch .LBB0_527
